# st2 RG-LRU inter-chunk carry: 8 chunk pairs loaded together per loop trip (1 round trip instead of 8)
# speedup vs baseline: 1.0114x; 1.0025x over previous
.LBB0_813:
	v_lshl_add_u64 v[4:5], v[0:1], 0, s[2:3]
	s_mov_b32 s0, 0x6a31000
	v_add_co_u32_e32 v6, vcc, s0, v4
	s_nop 1
	v_addc_co_u32_e32 v7, vcc, 0, v5, vcc
	s_mov_b32 s0, 0x6a11000
	v_add_co_u32_e32 v8, vcc, s0, v4
	s_nop 1
	v_addc_co_u32_e32 v9, vcc, 0, v5, vcc
	s_mov_b32 s0, 0x69f1000
	v_add_co_u32_e32 v10, vcc, s0, v4
	s_nop 1
	v_addc_co_u32_e32 v11, vcc, 0, v5, vcc
	s_mov_b32 s0, 0x6a32000
	v_add_co_u32_e32 v62, vcc, s0, v4
	s_nop 1
	v_addc_co_u32_e32 v63, vcc, 0, v5, vcc
	s_mov_b32 s0, 0x6a12000
	v_add_co_u32_e32 v64, vcc, s0, v4
	s_nop 1
	v_addc_co_u32_e32 v65, vcc, 0, v5, vcc
	s_mov_b32 s0, 0x69f2000
	v_add_co_u32_e32 v66, vcc, s0, v4
	s_nop 1
	v_addc_co_u32_e32 v67, vcc, 0, v5, vcc
	global_load_dword v128, v[8:9], off
	global_load_dword v129, v[8:9], off offset:1024
	global_load_dword v130, v[8:9], off offset:2048
	global_load_dword v131, v[8:9], off offset:3072
	global_load_dword v136, v[10:11], off
	global_load_dword v137, v[10:11], off offset:1024
	global_load_dword v138, v[10:11], off offset:2048
	global_load_dword v139, v[10:11], off offset:3072
	global_load_dword v132, v[64:65], off
	global_load_dword v133, v[64:65], off offset:1024
	global_load_dword v134, v[64:65], off offset:2048
	global_load_dword v135, v[64:65], off offset:3072
	global_load_dword v140, v[66:67], off
	global_load_dword v141, v[66:67], off offset:1024
	global_load_dword v142, v[66:67], off offset:2048
	global_load_dword v143, v[66:67], off offset:3072
	global_store_dword v[6:7], v3, off
	s_add_u32 s2, s2, 0x2000
	s_addc_u32 s3, s3, 0
	s_cmp_lg_u32 s2, 0x10000
	s_waitcnt vmcnt(0)
	v_fmac_f32_e32 v136, v3, v128
	global_store_dword v[6:7], v136, off offset:1024
	v_fmac_f32_e32 v137, v136, v129
	global_store_dword v[6:7], v137, off offset:2048
	v_fmac_f32_e32 v138, v137, v130
	global_store_dword v[6:7], v138, off offset:3072
	v_fmac_f32_e32 v139, v138, v131
	global_store_dword v[62:63], v139, off
	v_fmac_f32_e32 v140, v139, v132
	global_store_dword v[62:63], v140, off offset:1024
	v_fmac_f32_e32 v141, v140, v133
	global_store_dword v[62:63], v141, off offset:2048
	v_fmac_f32_e32 v142, v141, v134
	global_store_dword v[62:63], v142, off offset:3072
	v_fmac_f32_e32 v143, v142, v135
	v_mov_b32_e32 v3, v143
	s_cbranch_scc1 .LBB0_813
